# v37: + P3 generic epilogue branch hand-written (column class per 32-col group, pipelined rs reads, straight-line stores)
# speedup vs baseline: 1.1446x; 1.0133x over previous
.LBB0_1511:
	v_lshl_or_b32 v138, v129, 2, v136
	v_or_b32_e32 v140, v130, v142
	v_cmp_ne_u32_e32 vcc, 6, v128
	v_add_u32_e32 v139, s18, v138
	v_lshl_add_u32 v141, v138, 2, v200
	s_and_saveexec_b64 s[6:7], vcc
	s_xor_b64 s[8:9], exec, s[6:7]
	s_cbranch_execz .LBB0_2153
	s_mov_b64 s[48:49], exec
	v_readfirstlane_b32 s12, v140
	s_and_b32 s12, s12, 0xffffffe0
	v_mov_b32_e32 v160, v140
	s_cmpk_lt_u32 s12, 0x7a0
	s_cselect_b32 s14, s42, s58
	s_cselect_b32 s15, s43, s59
	s_cselect_b32 s13, 12, 10
	s_cselect_b32 s16, 0, 0x7b0
	s_lshl_b32 s17, 1, s13
	s_mul_i32 s19, s17, 5
	v_subrev_u32_e32 v161, s16, v160
	v_lshlrev_b32_e32 v161, 1, v161
	v_lshlrev_b32_e32 v162, s13, v139
	v_add_u32_e32 v162, v162, v161
	v_add_u32_e32 v161, 0xfffff860, v160
	v_cmp_lt_u32_e64 s[44:45], 15, v161
	v_cmp_gt_u32_e32 vcc, 0x9b0, v160
	s_and_b64 s[44:45], s[44:45], vcc
	v_cmp_gt_u32_e32 vcc, 16, v161
	s_mov_b64 s[46:47], vcc
	v_lshlrev_b32_e32 v163, 6, v139
	v_lshl_add_u32 v163, v161, 2, v163
	s_mov_b64 exec, s[44:45]
	s_cbranch_execz .Lp3g_nb0
	ds_read_b128 v[176:179], v141 offset:0
	ds_read_b128 v[180:183], v141 offset:32
	ds_read_b128 v[184:187], v141 offset:64
	ds_read_b128 v[188:191], v141 offset:96
	ds_read_b128 v[210:213], v141 offset:128
	ds_read_b128 v[214:217], v141 offset:160
	ds_read_b128 v[218:221], v141 offset:192
	ds_read_b128 v[222:225], v141 offset:224
	s_waitcnt lgkmcnt(7)
	v_mul_f32_e32 v164, v112, v176
	v_mul_f32_e32 v165, v113, v177
	v_mul_f32_e32 v166, v114, v178
	v_mul_f32_e32 v167, v115, v179
	ds_read_b128 v[176:179], v141 offset:256
	v_cvt_pk_bf16_f32 v168, v164, v165
	v_cvt_pk_bf16_f32 v169, v166, v167
	global_store_short v162, v168, s[14:15]
	v_add_u32_e32 v162, s17, v162
	global_store_short_d16_hi v162, v168, s[14:15]
	v_add_u32_e32 v162, s17, v162
	global_store_short v162, v169, s[14:15]
	v_add_u32_e32 v162, s17, v162
	global_store_short_d16_hi v162, v169, s[14:15]
	v_add_u32_e32 v162, s19, v162
	s_waitcnt lgkmcnt(7)
	v_mul_f32_e32 v164, v116, v180
	v_mul_f32_e32 v165, v117, v181
	v_mul_f32_e32 v166, v118, v182
	v_mul_f32_e32 v167, v119, v183
	ds_read_b128 v[180:183], v141 offset:288
	v_cvt_pk_bf16_f32 v170, v164, v165
	v_cvt_pk_bf16_f32 v171, v166, v167
	global_store_short v162, v170, s[14:15]
	v_add_u32_e32 v162, s17, v162
	global_store_short_d16_hi v162, v170, s[14:15]
	v_add_u32_e32 v162, s17, v162
	global_store_short v162, v171, s[14:15]
	v_add_u32_e32 v162, s17, v162
	global_store_short_d16_hi v162, v171, s[14:15]
	v_add_u32_e32 v162, s19, v162
	s_waitcnt lgkmcnt(7)
	v_mul_f32_e32 v164, v120, v184
	v_mul_f32_e32 v165, v121, v185
	v_mul_f32_e32 v166, v122, v186
	v_mul_f32_e32 v167, v123, v187
	ds_read_b128 v[184:187], v141 offset:320
	v_cvt_pk_bf16_f32 v172, v164, v165
	v_cvt_pk_bf16_f32 v173, v166, v167
	global_store_short v162, v172, s[14:15]
	v_add_u32_e32 v162, s17, v162
	global_store_short_d16_hi v162, v172, s[14:15]
	v_add_u32_e32 v162, s17, v162
	global_store_short v162, v173, s[14:15]
	v_add_u32_e32 v162, s17, v162
	global_store_short_d16_hi v162, v173, s[14:15]
	v_add_u32_e32 v162, s19, v162
	s_waitcnt lgkmcnt(7)
	v_mul_f32_e32 v164, v124, v188
	v_mul_f32_e32 v165, v125, v189
	v_mul_f32_e32 v166, v126, v190
	v_mul_f32_e32 v167, v127, v191
	ds_read_b128 v[188:191], v141 offset:352
	v_cvt_pk_bf16_f32 v174, v164, v165
	v_cvt_pk_bf16_f32 v175, v166, v167
	global_store_short v162, v174, s[14:15]
	v_add_u32_e32 v162, s17, v162
	global_store_short_d16_hi v162, v174, s[14:15]
	v_add_u32_e32 v162, s17, v162
	global_store_short v162, v175, s[14:15]
	v_add_u32_e32 v162, s17, v162
	global_store_short_d16_hi v162, v175, s[14:15]
	v_add_u32_e32 v162, s19, v162
	s_waitcnt lgkmcnt(7)
	v_mul_f32_e32 v164, v96, v210
	v_mul_f32_e32 v165, v97, v211
	v_mul_f32_e32 v166, v98, v212
	v_mul_f32_e32 v167, v99, v213
	ds_read_b128 v[210:213], v141 offset:384
	v_cvt_pk_bf16_f32 v168, v164, v165
	v_cvt_pk_bf16_f32 v169, v166, v167
	global_store_short v162, v168, s[14:15]
	v_add_u32_e32 v162, s17, v162
	global_store_short_d16_hi v162, v168, s[14:15]
	v_add_u32_e32 v162, s17, v162
	global_store_short v162, v169, s[14:15]
	v_add_u32_e32 v162, s17, v162
	global_store_short_d16_hi v162, v169, s[14:15]
	v_add_u32_e32 v162, s19, v162
	s_waitcnt lgkmcnt(7)
	v_mul_f32_e32 v164, v100, v214
	v_mul_f32_e32 v165, v101, v215
	v_mul_f32_e32 v166, v102, v216
	v_mul_f32_e32 v167, v103, v217
	ds_read_b128 v[214:217], v141 offset:416
	v_cvt_pk_bf16_f32 v170, v164, v165
	v_cvt_pk_bf16_f32 v171, v166, v167
	global_store_short v162, v170, s[14:15]
	v_add_u32_e32 v162, s17, v162
	global_store_short_d16_hi v162, v170, s[14:15]
	v_add_u32_e32 v162, s17, v162
	global_store_short v162, v171, s[14:15]
	v_add_u32_e32 v162, s17, v162
	global_store_short_d16_hi v162, v171, s[14:15]
	v_add_u32_e32 v162, s19, v162
	s_waitcnt lgkmcnt(7)
	v_mul_f32_e32 v164, v104, v218
	v_mul_f32_e32 v165, v105, v219
	v_mul_f32_e32 v166, v106, v220
	v_mul_f32_e32 v167, v107, v221
	ds_read_b128 v[218:221], v141 offset:448
	v_cvt_pk_bf16_f32 v172, v164, v165
	v_cvt_pk_bf16_f32 v173, v166, v167
	global_store_short v162, v172, s[14:15]
	v_add_u32_e32 v162, s17, v162
	global_store_short_d16_hi v162, v172, s[14:15]
	v_add_u32_e32 v162, s17, v162
	global_store_short v162, v173, s[14:15]
	v_add_u32_e32 v162, s17, v162
	global_store_short_d16_hi v162, v173, s[14:15]
	v_add_u32_e32 v162, s19, v162
	s_waitcnt lgkmcnt(7)
	v_mul_f32_e32 v164, v108, v222
	v_mul_f32_e32 v165, v109, v223
	v_mul_f32_e32 v166, v110, v224
	v_mul_f32_e32 v167, v111, v225
	ds_read_b128 v[222:225], v141 offset:480
	v_cvt_pk_bf16_f32 v174, v164, v165
	v_cvt_pk_bf16_f32 v175, v166, v167
	global_store_short v162, v174, s[14:15]
	v_add_u32_e32 v162, s17, v162
	global_store_short_d16_hi v162, v174, s[14:15]
	v_add_u32_e32 v162, s17, v162
	global_store_short v162, v175, s[14:15]
	v_add_u32_e32 v162, s17, v162
	global_store_short_d16_hi v162, v175, s[14:15]
	v_add_u32_e32 v162, s19, v162
	s_waitcnt lgkmcnt(7)
	v_mul_f32_e32 v164, v80, v176
	v_mul_f32_e32 v165, v81, v177
	v_mul_f32_e32 v166, v82, v178
	v_mul_f32_e32 v167, v83, v179
	v_cvt_pk_bf16_f32 v168, v164, v165
	v_cvt_pk_bf16_f32 v169, v166, v167
	global_store_short v162, v168, s[14:15]
	v_add_u32_e32 v162, s17, v162
	global_store_short_d16_hi v162, v168, s[14:15]
	v_add_u32_e32 v162, s17, v162
	global_store_short v162, v169, s[14:15]
	v_add_u32_e32 v162, s17, v162
	global_store_short_d16_hi v162, v169, s[14:15]
	v_add_u32_e32 v162, s19, v162
	s_waitcnt lgkmcnt(6)
	v_mul_f32_e32 v164, v84, v180
	v_mul_f32_e32 v165, v85, v181
	v_mul_f32_e32 v166, v86, v182
	v_mul_f32_e32 v167, v87, v183
	v_cvt_pk_bf16_f32 v170, v164, v165
	v_cvt_pk_bf16_f32 v171, v166, v167
	global_store_short v162, v170, s[14:15]
	v_add_u32_e32 v162, s17, v162
	global_store_short_d16_hi v162, v170, s[14:15]
	v_add_u32_e32 v162, s17, v162
	global_store_short v162, v171, s[14:15]
	v_add_u32_e32 v162, s17, v162
	global_store_short_d16_hi v162, v171, s[14:15]
	v_add_u32_e32 v162, s19, v162
	s_waitcnt lgkmcnt(5)
	v_mul_f32_e32 v164, v88, v184
	v_mul_f32_e32 v165, v89, v185
	v_mul_f32_e32 v166, v90, v186
	v_mul_f32_e32 v167, v91, v187
	v_cvt_pk_bf16_f32 v172, v164, v165
	v_cvt_pk_bf16_f32 v173, v166, v167
	global_store_short v162, v172, s[14:15]
	v_add_u32_e32 v162, s17, v162
	global_store_short_d16_hi v162, v172, s[14:15]
	v_add_u32_e32 v162, s17, v162
	global_store_short v162, v173, s[14:15]
	v_add_u32_e32 v162, s17, v162
	global_store_short_d16_hi v162, v173, s[14:15]
	v_add_u32_e32 v162, s19, v162
	s_waitcnt lgkmcnt(4)
	v_mul_f32_e32 v164, v92, v188
	v_mul_f32_e32 v165, v93, v189
	v_mul_f32_e32 v166, v94, v190
	v_mul_f32_e32 v167, v95, v191
	v_cvt_pk_bf16_f32 v174, v164, v165
	v_cvt_pk_bf16_f32 v175, v166, v167
	global_store_short v162, v174, s[14:15]
	v_add_u32_e32 v162, s17, v162
	global_store_short_d16_hi v162, v174, s[14:15]
	v_add_u32_e32 v162, s17, v162
	global_store_short v162, v175, s[14:15]
	v_add_u32_e32 v162, s17, v162
	global_store_short_d16_hi v162, v175, s[14:15]
	v_add_u32_e32 v162, s19, v162
	s_waitcnt lgkmcnt(3)
	v_mul_f32_e32 v164, v64, v210
	v_mul_f32_e32 v165, v65, v211
	v_mul_f32_e32 v166, v66, v212
	v_mul_f32_e32 v167, v67, v213
	v_cvt_pk_bf16_f32 v168, v164, v165
	v_cvt_pk_bf16_f32 v169, v166, v167
	global_store_short v162, v168, s[14:15]
	v_add_u32_e32 v162, s17, v162
	global_store_short_d16_hi v162, v168, s[14:15]
	v_add_u32_e32 v162, s17, v162
	global_store_short v162, v169, s[14:15]
	v_add_u32_e32 v162, s17, v162
	global_store_short_d16_hi v162, v169, s[14:15]
	v_add_u32_e32 v162, s19, v162
	s_waitcnt lgkmcnt(2)
	v_mul_f32_e32 v164, v68, v214
	v_mul_f32_e32 v165, v69, v215
	v_mul_f32_e32 v166, v70, v216
	v_mul_f32_e32 v167, v71, v217
	v_cvt_pk_bf16_f32 v170, v164, v165
	v_cvt_pk_bf16_f32 v171, v166, v167
	global_store_short v162, v170, s[14:15]
	v_add_u32_e32 v162, s17, v162
	global_store_short_d16_hi v162, v170, s[14:15]
	v_add_u32_e32 v162, s17, v162
	global_store_short v162, v171, s[14:15]
	v_add_u32_e32 v162, s17, v162
	global_store_short_d16_hi v162, v171, s[14:15]
	v_add_u32_e32 v162, s19, v162
	s_waitcnt lgkmcnt(1)
	v_mul_f32_e32 v164, v72, v218
	v_mul_f32_e32 v165, v73, v219
	v_mul_f32_e32 v166, v74, v220
	v_mul_f32_e32 v167, v75, v221
	v_cvt_pk_bf16_f32 v172, v164, v165
	v_cvt_pk_bf16_f32 v173, v166, v167
	global_store_short v162, v172, s[14:15]
	v_add_u32_e32 v162, s17, v162
	global_store_short_d16_hi v162, v172, s[14:15]
	v_add_u32_e32 v162, s17, v162
	global_store_short v162, v173, s[14:15]
	v_add_u32_e32 v162, s17, v162
	global_store_short_d16_hi v162, v173, s[14:15]
	v_add_u32_e32 v162, s19, v162
	s_waitcnt lgkmcnt(0)
	v_mul_f32_e32 v164, v76, v222
	v_mul_f32_e32 v165, v77, v223
	v_mul_f32_e32 v166, v78, v224
	v_mul_f32_e32 v167, v79, v225
	v_cvt_pk_bf16_f32 v174, v164, v165
	v_cvt_pk_bf16_f32 v175, v166, v167
	global_store_short v162, v174, s[14:15]
	v_add_u32_e32 v162, s17, v162
	global_store_short_d16_hi v162, v174, s[14:15]
	v_add_u32_e32 v162, s17, v162
	global_store_short v162, v175, s[14:15]
	v_add_u32_e32 v162, s17, v162
	global_store_short_d16_hi v162, v175, s[14:15]
.Lp3g_nb0:
	s_mov_b64 exec, s[46:47]
	s_cbranch_execz .Lp3g_na0
	ds_read_b128 v[176:179], v141 offset:0
	ds_read_b128 v[180:183], v141 offset:32
	ds_read_b128 v[184:187], v141 offset:64
	ds_read_b128 v[188:191], v141 offset:96
	ds_read_b128 v[210:213], v141 offset:128
	ds_read_b128 v[214:217], v141 offset:160
	ds_read_b128 v[218:221], v141 offset:192
	ds_read_b128 v[222:225], v141 offset:224
	s_waitcnt lgkmcnt(7)
	v_mul_f32_e32 v168, v112, v176
	v_mul_f32_e32 v169, v113, v177
	v_mul_f32_e32 v170, v114, v178
	v_mul_f32_e32 v171, v115, v179
	ds_read_b128 v[176:179], v141 offset:256
	global_store_dword v163, v168, s[78:79]
	v_add_u32_e32 v163, 64, v163
	global_store_dword v163, v169, s[78:79]
	v_add_u32_e32 v163, 64, v163
	global_store_dword v163, v170, s[78:79]
	v_add_u32_e32 v163, 64, v163
	global_store_dword v163, v171, s[78:79]
	v_add_u32_e32 v163, 0x140, v163
	s_waitcnt lgkmcnt(7)
	v_mul_f32_e32 v172, v116, v180
	v_mul_f32_e32 v173, v117, v181
	v_mul_f32_e32 v174, v118, v182
	v_mul_f32_e32 v175, v119, v183
	ds_read_b128 v[180:183], v141 offset:288
	global_store_dword v163, v172, s[78:79]
	v_add_u32_e32 v163, 64, v163
	global_store_dword v163, v173, s[78:79]
	v_add_u32_e32 v163, 64, v163
	global_store_dword v163, v174, s[78:79]
	v_add_u32_e32 v163, 64, v163
	global_store_dword v163, v175, s[78:79]
	v_add_u32_e32 v163, 0x140, v163
	s_waitcnt lgkmcnt(7)
	v_mul_f32_e32 v168, v120, v184
	v_mul_f32_e32 v169, v121, v185
	v_mul_f32_e32 v170, v122, v186
	v_mul_f32_e32 v171, v123, v187
	ds_read_b128 v[184:187], v141 offset:320
	global_store_dword v163, v168, s[78:79]
	v_add_u32_e32 v163, 64, v163
	global_store_dword v163, v169, s[78:79]
	v_add_u32_e32 v163, 64, v163
	global_store_dword v163, v170, s[78:79]
	v_add_u32_e32 v163, 64, v163
	global_store_dword v163, v171, s[78:79]
	v_add_u32_e32 v163, 0x140, v163
	s_waitcnt lgkmcnt(7)
	v_mul_f32_e32 v172, v124, v188
	v_mul_f32_e32 v173, v125, v189
	v_mul_f32_e32 v174, v126, v190
	v_mul_f32_e32 v175, v127, v191
	ds_read_b128 v[188:191], v141 offset:352
	global_store_dword v163, v172, s[78:79]
	v_add_u32_e32 v163, 64, v163
	global_store_dword v163, v173, s[78:79]
	v_add_u32_e32 v163, 64, v163
	global_store_dword v163, v174, s[78:79]
	v_add_u32_e32 v163, 64, v163
	global_store_dword v163, v175, s[78:79]
	v_add_u32_e32 v163, 0x140, v163
	s_waitcnt lgkmcnt(7)
	v_mul_f32_e32 v168, v96, v210
	v_mul_f32_e32 v169, v97, v211
	v_mul_f32_e32 v170, v98, v212
	v_mul_f32_e32 v171, v99, v213
	ds_read_b128 v[210:213], v141 offset:384
	global_store_dword v163, v168, s[78:79]
	v_add_u32_e32 v163, 64, v163
	global_store_dword v163, v169, s[78:79]
	v_add_u32_e32 v163, 64, v163
	global_store_dword v163, v170, s[78:79]
	v_add_u32_e32 v163, 64, v163
	global_store_dword v163, v171, s[78:79]
	v_add_u32_e32 v163, 0x140, v163
	s_waitcnt lgkmcnt(7)
	v_mul_f32_e32 v172, v100, v214
	v_mul_f32_e32 v173, v101, v215
	v_mul_f32_e32 v174, v102, v216
	v_mul_f32_e32 v175, v103, v217
	ds_read_b128 v[214:217], v141 offset:416
	global_store_dword v163, v172, s[78:79]
	v_add_u32_e32 v163, 64, v163
	global_store_dword v163, v173, s[78:79]
	v_add_u32_e32 v163, 64, v163
	global_store_dword v163, v174, s[78:79]
	v_add_u32_e32 v163, 64, v163
	global_store_dword v163, v175, s[78:79]
	v_add_u32_e32 v163, 0x140, v163
	s_waitcnt lgkmcnt(7)
	v_mul_f32_e32 v168, v104, v218
	v_mul_f32_e32 v169, v105, v219
	v_mul_f32_e32 v170, v106, v220
	v_mul_f32_e32 v171, v107, v221
	ds_read_b128 v[218:221], v141 offset:448
	global_store_dword v163, v168, s[78:79]
	v_add_u32_e32 v163, 64, v163
	global_store_dword v163, v169, s[78:79]
	v_add_u32_e32 v163, 64, v163
	global_store_dword v163, v170, s[78:79]
	v_add_u32_e32 v163, 64, v163
	global_store_dword v163, v171, s[78:79]
	v_add_u32_e32 v163, 0x140, v163
	s_waitcnt lgkmcnt(7)
	v_mul_f32_e32 v172, v108, v222
	v_mul_f32_e32 v173, v109, v223
	v_mul_f32_e32 v174, v110, v224
	v_mul_f32_e32 v175, v111, v225
	ds_read_b128 v[222:225], v141 offset:480
	global_store_dword v163, v172, s[78:79]
	v_add_u32_e32 v163, 64, v163
	global_store_dword v163, v173, s[78:79]
	v_add_u32_e32 v163, 64, v163
	global_store_dword v163, v174, s[78:79]
	v_add_u32_e32 v163, 64, v163
	global_store_dword v163, v175, s[78:79]
	v_add_u32_e32 v163, 0x140, v163
	s_waitcnt lgkmcnt(7)
	v_mul_f32_e32 v168, v80, v176
	v_mul_f32_e32 v169, v81, v177
	v_mul_f32_e32 v170, v82, v178
	v_mul_f32_e32 v171, v83, v179
	global_store_dword v163, v168, s[78:79]
	v_add_u32_e32 v163, 64, v163
	global_store_dword v163, v169, s[78:79]
	v_add_u32_e32 v163, 64, v163
	global_store_dword v163, v170, s[78:79]
	v_add_u32_e32 v163, 64, v163
	global_store_dword v163, v171, s[78:79]
	v_add_u32_e32 v163, 0x140, v163
	s_waitcnt lgkmcnt(6)
	v_mul_f32_e32 v172, v84, v180
	v_mul_f32_e32 v173, v85, v181
	v_mul_f32_e32 v174, v86, v182
	v_mul_f32_e32 v175, v87, v183
	global_store_dword v163, v172, s[78:79]
	v_add_u32_e32 v163, 64, v163
	global_store_dword v163, v173, s[78:79]
	v_add_u32_e32 v163, 64, v163
	global_store_dword v163, v174, s[78:79]
	v_add_u32_e32 v163, 64, v163
	global_store_dword v163, v175, s[78:79]
	v_add_u32_e32 v163, 0x140, v163
	s_waitcnt lgkmcnt(5)
	v_mul_f32_e32 v168, v88, v184
	v_mul_f32_e32 v169, v89, v185
	v_mul_f32_e32 v170, v90, v186
	v_mul_f32_e32 v171, v91, v187
	global_store_dword v163, v168, s[78:79]
	v_add_u32_e32 v163, 64, v163
	global_store_dword v163, v169, s[78:79]
	v_add_u32_e32 v163, 64, v163
	global_store_dword v163, v170, s[78:79]
	v_add_u32_e32 v163, 64, v163
	global_store_dword v163, v171, s[78:79]
	v_add_u32_e32 v163, 0x140, v163
	s_waitcnt lgkmcnt(4)
	v_mul_f32_e32 v172, v92, v188
	v_mul_f32_e32 v173, v93, v189
	v_mul_f32_e32 v174, v94, v190
	v_mul_f32_e32 v175, v95, v191
	global_store_dword v163, v172, s[78:79]
	v_add_u32_e32 v163, 64, v163
	global_store_dword v163, v173, s[78:79]
	v_add_u32_e32 v163, 64, v163
	global_store_dword v163, v174, s[78:79]
	v_add_u32_e32 v163, 64, v163
	global_store_dword v163, v175, s[78:79]
	v_add_u32_e32 v163, 0x140, v163
	s_waitcnt lgkmcnt(3)
	v_mul_f32_e32 v168, v64, v210
	v_mul_f32_e32 v169, v65, v211
	v_mul_f32_e32 v170, v66, v212
	v_mul_f32_e32 v171, v67, v213
	global_store_dword v163, v168, s[78:79]
	v_add_u32_e32 v163, 64, v163
	global_store_dword v163, v169, s[78:79]
	v_add_u32_e32 v163, 64, v163
	global_store_dword v163, v170, s[78:79]
	v_add_u32_e32 v163, 64, v163
	global_store_dword v163, v171, s[78:79]
	v_add_u32_e32 v163, 0x140, v163
	s_waitcnt lgkmcnt(2)
	v_mul_f32_e32 v172, v68, v214
	v_mul_f32_e32 v173, v69, v215
	v_mul_f32_e32 v174, v70, v216
	v_mul_f32_e32 v175, v71, v217
	global_store_dword v163, v172, s[78:79]
	v_add_u32_e32 v163, 64, v163
	global_store_dword v163, v173, s[78:79]
	v_add_u32_e32 v163, 64, v163
	global_store_dword v163, v174, s[78:79]
	v_add_u32_e32 v163, 64, v163
	global_store_dword v163, v175, s[78:79]
	v_add_u32_e32 v163, 0x140, v163
	s_waitcnt lgkmcnt(1)
	v_mul_f32_e32 v168, v72, v218
	v_mul_f32_e32 v169, v73, v219
	v_mul_f32_e32 v170, v74, v220
	v_mul_f32_e32 v171, v75, v221
	global_store_dword v163, v168, s[78:79]
	v_add_u32_e32 v163, 64, v163
	global_store_dword v163, v169, s[78:79]
	v_add_u32_e32 v163, 64, v163
	global_store_dword v163, v170, s[78:79]
	v_add_u32_e32 v163, 64, v163
	global_store_dword v163, v171, s[78:79]
	v_add_u32_e32 v163, 0x140, v163
	s_waitcnt lgkmcnt(0)
	v_mul_f32_e32 v172, v76, v222
	v_mul_f32_e32 v173, v77, v223
	v_mul_f32_e32 v174, v78, v224
	v_mul_f32_e32 v175, v79, v225
	global_store_dword v163, v172, s[78:79]
	v_add_u32_e32 v163, 64, v163
	global_store_dword v163, v173, s[78:79]
	v_add_u32_e32 v163, 64, v163
	global_store_dword v163, v174, s[78:79]
	v_add_u32_e32 v163, 64, v163
	global_store_dword v163, v175, s[78:79]
.Lp3g_na0:
	s_mov_b64 exec, s[48:49]

.LBB0_2155:
	s_or_b64 exec, exec, s[6:7]
	s_mov_b64 s[48:49], exec
	v_readfirstlane_b32 s12, v140
	s_and_b32 s12, s12, 0xffffffe0
	s_add_i32 s12, s12, 32
	v_add_u32_e32 v160, 32, v140
	s_cmpk_lt_u32 s12, 0x7a0
	s_cselect_b32 s14, s42, s58
	s_cselect_b32 s15, s43, s59
	s_cselect_b32 s13, 12, 10
	s_cselect_b32 s16, 0, 0x7b0
	s_lshl_b32 s17, 1, s13
	s_mul_i32 s19, s17, 5
	v_subrev_u32_e32 v161, s16, v160
	v_lshlrev_b32_e32 v161, 1, v161
	v_lshlrev_b32_e32 v162, s13, v139
	v_add_u32_e32 v162, v162, v161
	v_add_u32_e32 v161, 0xfffff860, v160
	v_cmp_lt_u32_e64 s[44:45], 15, v161
	v_cmp_gt_u32_e32 vcc, 0x9b0, v160
	s_and_b64 s[44:45], s[44:45], vcc
	v_cmp_gt_u32_e32 vcc, 16, v161
	s_mov_b64 s[46:47], vcc
	v_lshlrev_b32_e32 v163, 6, v139
	v_lshl_add_u32 v163, v161, 2, v163
	s_mov_b64 exec, s[44:45]
	s_cbranch_execz .Lp3g_nb1
	ds_read_b128 v[176:179], v141 offset:0
	ds_read_b128 v[180:183], v141 offset:32
	ds_read_b128 v[184:187], v141 offset:64
	ds_read_b128 v[188:191], v141 offset:96
	ds_read_b128 v[210:213], v141 offset:128
	ds_read_b128 v[214:217], v141 offset:160
	ds_read_b128 v[218:221], v141 offset:192
	ds_read_b128 v[222:225], v141 offset:224
	s_waitcnt lgkmcnt(7)
	v_mul_f32_e32 v164, v48, v176
	v_mul_f32_e32 v165, v49, v177
	v_mul_f32_e32 v166, v50, v178
	v_mul_f32_e32 v167, v51, v179
	ds_read_b128 v[176:179], v141 offset:256
	v_cvt_pk_bf16_f32 v168, v164, v165
	v_cvt_pk_bf16_f32 v169, v166, v167
	global_store_short v162, v168, s[14:15]
	v_add_u32_e32 v162, s17, v162
	global_store_short_d16_hi v162, v168, s[14:15]
	v_add_u32_e32 v162, s17, v162
	global_store_short v162, v169, s[14:15]
	v_add_u32_e32 v162, s17, v162
	global_store_short_d16_hi v162, v169, s[14:15]
	v_add_u32_e32 v162, s19, v162
	s_waitcnt lgkmcnt(7)
	v_mul_f32_e32 v164, v52, v180
	v_mul_f32_e32 v165, v53, v181
	v_mul_f32_e32 v166, v54, v182
	v_mul_f32_e32 v167, v55, v183
	ds_read_b128 v[180:183], v141 offset:288
	v_cvt_pk_bf16_f32 v170, v164, v165
	v_cvt_pk_bf16_f32 v171, v166, v167
	global_store_short v162, v170, s[14:15]
	v_add_u32_e32 v162, s17, v162
	global_store_short_d16_hi v162, v170, s[14:15]
	v_add_u32_e32 v162, s17, v162
	global_store_short v162, v171, s[14:15]
	v_add_u32_e32 v162, s17, v162
	global_store_short_d16_hi v162, v171, s[14:15]
	v_add_u32_e32 v162, s19, v162
	s_waitcnt lgkmcnt(7)
	v_mul_f32_e32 v164, v56, v184
	v_mul_f32_e32 v165, v57, v185
	v_mul_f32_e32 v166, v58, v186
	v_mul_f32_e32 v167, v59, v187
	ds_read_b128 v[184:187], v141 offset:320
	v_cvt_pk_bf16_f32 v172, v164, v165
	v_cvt_pk_bf16_f32 v173, v166, v167
	global_store_short v162, v172, s[14:15]
	v_add_u32_e32 v162, s17, v162
	global_store_short_d16_hi v162, v172, s[14:15]
	v_add_u32_e32 v162, s17, v162
	global_store_short v162, v173, s[14:15]
	v_add_u32_e32 v162, s17, v162
	global_store_short_d16_hi v162, v173, s[14:15]
	v_add_u32_e32 v162, s19, v162
	s_waitcnt lgkmcnt(7)
	v_mul_f32_e32 v164, v60, v188
	v_mul_f32_e32 v165, v61, v189
	v_mul_f32_e32 v166, v62, v190
	v_mul_f32_e32 v167, v63, v191
	ds_read_b128 v[188:191], v141 offset:352
	v_cvt_pk_bf16_f32 v174, v164, v165
	v_cvt_pk_bf16_f32 v175, v166, v167
	global_store_short v162, v174, s[14:15]
	v_add_u32_e32 v162, s17, v162
	global_store_short_d16_hi v162, v174, s[14:15]
	v_add_u32_e32 v162, s17, v162
	global_store_short v162, v175, s[14:15]
	v_add_u32_e32 v162, s17, v162
	global_store_short_d16_hi v162, v175, s[14:15]
	v_add_u32_e32 v162, s19, v162
	s_waitcnt lgkmcnt(7)
	v_mul_f32_e32 v164, v32, v210
	v_mul_f32_e32 v165, v33, v211
	v_mul_f32_e32 v166, v34, v212
	v_mul_f32_e32 v167, v35, v213
	ds_read_b128 v[210:213], v141 offset:384
	v_cvt_pk_bf16_f32 v168, v164, v165
	v_cvt_pk_bf16_f32 v169, v166, v167
	global_store_short v162, v168, s[14:15]
	v_add_u32_e32 v162, s17, v162
	global_store_short_d16_hi v162, v168, s[14:15]
	v_add_u32_e32 v162, s17, v162
	global_store_short v162, v169, s[14:15]
	v_add_u32_e32 v162, s17, v162
	global_store_short_d16_hi v162, v169, s[14:15]
	v_add_u32_e32 v162, s19, v162
	s_waitcnt lgkmcnt(7)
	v_mul_f32_e32 v164, v36, v214
	v_mul_f32_e32 v165, v37, v215
	v_mul_f32_e32 v166, v38, v216
	v_mul_f32_e32 v167, v39, v217
	ds_read_b128 v[214:217], v141 offset:416
	v_cvt_pk_bf16_f32 v170, v164, v165
	v_cvt_pk_bf16_f32 v171, v166, v167
	global_store_short v162, v170, s[14:15]
	v_add_u32_e32 v162, s17, v162
	global_store_short_d16_hi v162, v170, s[14:15]
	v_add_u32_e32 v162, s17, v162
	global_store_short v162, v171, s[14:15]
	v_add_u32_e32 v162, s17, v162
	global_store_short_d16_hi v162, v171, s[14:15]
	v_add_u32_e32 v162, s19, v162
	s_waitcnt lgkmcnt(7)
	v_mul_f32_e32 v164, v40, v218
	v_mul_f32_e32 v165, v41, v219
	v_mul_f32_e32 v166, v42, v220
	v_mul_f32_e32 v167, v43, v221
	ds_read_b128 v[218:221], v141 offset:448
	v_cvt_pk_bf16_f32 v172, v164, v165
	v_cvt_pk_bf16_f32 v173, v166, v167
	global_store_short v162, v172, s[14:15]
	v_add_u32_e32 v162, s17, v162
	global_store_short_d16_hi v162, v172, s[14:15]
	v_add_u32_e32 v162, s17, v162
	global_store_short v162, v173, s[14:15]
	v_add_u32_e32 v162, s17, v162
	global_store_short_d16_hi v162, v173, s[14:15]
	v_add_u32_e32 v162, s19, v162
	s_waitcnt lgkmcnt(7)
	v_mul_f32_e32 v164, v44, v222
	v_mul_f32_e32 v165, v45, v223
	v_mul_f32_e32 v166, v46, v224
	v_mul_f32_e32 v167, v47, v225
	ds_read_b128 v[222:225], v141 offset:480
	v_cvt_pk_bf16_f32 v174, v164, v165
	v_cvt_pk_bf16_f32 v175, v166, v167
	global_store_short v162, v174, s[14:15]
	v_add_u32_e32 v162, s17, v162
	global_store_short_d16_hi v162, v174, s[14:15]
	v_add_u32_e32 v162, s17, v162
	global_store_short v162, v175, s[14:15]
	v_add_u32_e32 v162, s17, v162
	global_store_short_d16_hi v162, v175, s[14:15]
	v_add_u32_e32 v162, s19, v162
	s_waitcnt lgkmcnt(7)
	v_mul_f32_e32 v164, v16, v176
	v_mul_f32_e32 v165, v17, v177
	v_mul_f32_e32 v166, v18, v178
	v_mul_f32_e32 v167, v19, v179
	v_cvt_pk_bf16_f32 v168, v164, v165
	v_cvt_pk_bf16_f32 v169, v166, v167
	global_store_short v162, v168, s[14:15]
	v_add_u32_e32 v162, s17, v162
	global_store_short_d16_hi v162, v168, s[14:15]
	v_add_u32_e32 v162, s17, v162
	global_store_short v162, v169, s[14:15]
	v_add_u32_e32 v162, s17, v162
	global_store_short_d16_hi v162, v169, s[14:15]
	v_add_u32_e32 v162, s19, v162
	s_waitcnt lgkmcnt(6)
	v_mul_f32_e32 v164, v20, v180
	v_mul_f32_e32 v165, v21, v181
	v_mul_f32_e32 v166, v22, v182
	v_mul_f32_e32 v167, v23, v183
	v_cvt_pk_bf16_f32 v170, v164, v165
	v_cvt_pk_bf16_f32 v171, v166, v167
	global_store_short v162, v170, s[14:15]
	v_add_u32_e32 v162, s17, v162
	global_store_short_d16_hi v162, v170, s[14:15]
	v_add_u32_e32 v162, s17, v162
	global_store_short v162, v171, s[14:15]
	v_add_u32_e32 v162, s17, v162
	global_store_short_d16_hi v162, v171, s[14:15]
	v_add_u32_e32 v162, s19, v162
	s_waitcnt lgkmcnt(5)
	v_mul_f32_e32 v164, v24, v184
	v_mul_f32_e32 v165, v25, v185
	v_mul_f32_e32 v166, v26, v186
	v_mul_f32_e32 v167, v27, v187
	v_cvt_pk_bf16_f32 v172, v164, v165
	v_cvt_pk_bf16_f32 v173, v166, v167
	global_store_short v162, v172, s[14:15]
	v_add_u32_e32 v162, s17, v162
	global_store_short_d16_hi v162, v172, s[14:15]
	v_add_u32_e32 v162, s17, v162
	global_store_short v162, v173, s[14:15]
	v_add_u32_e32 v162, s17, v162
	global_store_short_d16_hi v162, v173, s[14:15]
	v_add_u32_e32 v162, s19, v162
	s_waitcnt lgkmcnt(4)
	v_mul_f32_e32 v164, v28, v188
	v_mul_f32_e32 v165, v29, v189
	v_mul_f32_e32 v166, v30, v190
	v_mul_f32_e32 v167, v31, v191
	v_cvt_pk_bf16_f32 v174, v164, v165
	v_cvt_pk_bf16_f32 v175, v166, v167
	global_store_short v162, v174, s[14:15]
	v_add_u32_e32 v162, s17, v162
	global_store_short_d16_hi v162, v174, s[14:15]
	v_add_u32_e32 v162, s17, v162
	global_store_short v162, v175, s[14:15]
	v_add_u32_e32 v162, s17, v162
	global_store_short_d16_hi v162, v175, s[14:15]
	v_add_u32_e32 v162, s19, v162
	s_waitcnt lgkmcnt(3)
	v_mul_f32_e32 v164, v0, v210
	v_mul_f32_e32 v165, v1, v211
	v_mul_f32_e32 v166, v2, v212
	v_mul_f32_e32 v167, v3, v213
	v_cvt_pk_bf16_f32 v168, v164, v165
	v_cvt_pk_bf16_f32 v169, v166, v167
	global_store_short v162, v168, s[14:15]
	v_add_u32_e32 v162, s17, v162
	global_store_short_d16_hi v162, v168, s[14:15]
	v_add_u32_e32 v162, s17, v162
	global_store_short v162, v169, s[14:15]
	v_add_u32_e32 v162, s17, v162
	global_store_short_d16_hi v162, v169, s[14:15]
	v_add_u32_e32 v162, s19, v162
	s_waitcnt lgkmcnt(2)
	v_mul_f32_e32 v164, v4, v214
	v_mul_f32_e32 v165, v5, v215
	v_mul_f32_e32 v166, v6, v216
	v_mul_f32_e32 v167, v7, v217
	v_cvt_pk_bf16_f32 v170, v164, v165
	v_cvt_pk_bf16_f32 v171, v166, v167
	global_store_short v162, v170, s[14:15]
	v_add_u32_e32 v162, s17, v162
	global_store_short_d16_hi v162, v170, s[14:15]
	v_add_u32_e32 v162, s17, v162
	global_store_short v162, v171, s[14:15]
	v_add_u32_e32 v162, s17, v162
	global_store_short_d16_hi v162, v171, s[14:15]
	v_add_u32_e32 v162, s19, v162
	s_waitcnt lgkmcnt(1)
	v_mul_f32_e32 v164, v8, v218
	v_mul_f32_e32 v165, v9, v219
	v_mul_f32_e32 v166, v10, v220
	v_mul_f32_e32 v167, v11, v221
	v_cvt_pk_bf16_f32 v172, v164, v165
	v_cvt_pk_bf16_f32 v173, v166, v167
	global_store_short v162, v172, s[14:15]
	v_add_u32_e32 v162, s17, v162
	global_store_short_d16_hi v162, v172, s[14:15]
	v_add_u32_e32 v162, s17, v162
	global_store_short v162, v173, s[14:15]
	v_add_u32_e32 v162, s17, v162
	global_store_short_d16_hi v162, v173, s[14:15]
	v_add_u32_e32 v162, s19, v162
	s_waitcnt lgkmcnt(0)
	v_mul_f32_e32 v164, v12, v222
	v_mul_f32_e32 v165, v13, v223
	v_mul_f32_e32 v166, v14, v224
	v_mul_f32_e32 v167, v15, v225
	v_cvt_pk_bf16_f32 v174, v164, v165
	v_cvt_pk_bf16_f32 v175, v166, v167
	global_store_short v162, v174, s[14:15]
	v_add_u32_e32 v162, s17, v162
	global_store_short_d16_hi v162, v174, s[14:15]
	v_add_u32_e32 v162, s17, v162
	global_store_short v162, v175, s[14:15]
	v_add_u32_e32 v162, s17, v162
	global_store_short_d16_hi v162, v175, s[14:15]
.Lp3g_nb1:
	s_mov_b64 exec, s[46:47]
	s_cbranch_execz .Lp3g_na1
	ds_read_b128 v[176:179], v141 offset:0
	ds_read_b128 v[180:183], v141 offset:32
	ds_read_b128 v[184:187], v141 offset:64
	ds_read_b128 v[188:191], v141 offset:96
	ds_read_b128 v[210:213], v141 offset:128
	ds_read_b128 v[214:217], v141 offset:160
	ds_read_b128 v[218:221], v141 offset:192
	ds_read_b128 v[222:225], v141 offset:224
	s_waitcnt lgkmcnt(7)
	v_mul_f32_e32 v168, v48, v176
	v_mul_f32_e32 v169, v49, v177
	v_mul_f32_e32 v170, v50, v178
	v_mul_f32_e32 v171, v51, v179
	ds_read_b128 v[176:179], v141 offset:256
	global_store_dword v163, v168, s[78:79]
	v_add_u32_e32 v163, 64, v163
	global_store_dword v163, v169, s[78:79]
	v_add_u32_e32 v163, 64, v163
	global_store_dword v163, v170, s[78:79]
	v_add_u32_e32 v163, 64, v163
	global_store_dword v163, v171, s[78:79]
	v_add_u32_e32 v163, 0x140, v163
	s_waitcnt lgkmcnt(7)
	v_mul_f32_e32 v172, v52, v180
	v_mul_f32_e32 v173, v53, v181
	v_mul_f32_e32 v174, v54, v182
	v_mul_f32_e32 v175, v55, v183
	ds_read_b128 v[180:183], v141 offset:288
	global_store_dword v163, v172, s[78:79]
	v_add_u32_e32 v163, 64, v163
	global_store_dword v163, v173, s[78:79]
	v_add_u32_e32 v163, 64, v163
	global_store_dword v163, v174, s[78:79]
	v_add_u32_e32 v163, 64, v163
	global_store_dword v163, v175, s[78:79]
	v_add_u32_e32 v163, 0x140, v163
	s_waitcnt lgkmcnt(7)
	v_mul_f32_e32 v168, v56, v184
	v_mul_f32_e32 v169, v57, v185
	v_mul_f32_e32 v170, v58, v186
	v_mul_f32_e32 v171, v59, v187
	ds_read_b128 v[184:187], v141 offset:320
	global_store_dword v163, v168, s[78:79]
	v_add_u32_e32 v163, 64, v163
	global_store_dword v163, v169, s[78:79]
	v_add_u32_e32 v163, 64, v163
	global_store_dword v163, v170, s[78:79]
	v_add_u32_e32 v163, 64, v163
	global_store_dword v163, v171, s[78:79]
	v_add_u32_e32 v163, 0x140, v163
	s_waitcnt lgkmcnt(7)
	v_mul_f32_e32 v172, v60, v188
	v_mul_f32_e32 v173, v61, v189
	v_mul_f32_e32 v174, v62, v190
	v_mul_f32_e32 v175, v63, v191
	ds_read_b128 v[188:191], v141 offset:352
	global_store_dword v163, v172, s[78:79]
	v_add_u32_e32 v163, 64, v163
	global_store_dword v163, v173, s[78:79]
	v_add_u32_e32 v163, 64, v163
	global_store_dword v163, v174, s[78:79]
	v_add_u32_e32 v163, 64, v163
	global_store_dword v163, v175, s[78:79]
	v_add_u32_e32 v163, 0x140, v163
	s_waitcnt lgkmcnt(7)
	v_mul_f32_e32 v168, v32, v210
	v_mul_f32_e32 v169, v33, v211
	v_mul_f32_e32 v170, v34, v212
	v_mul_f32_e32 v171, v35, v213
	ds_read_b128 v[210:213], v141 offset:384
	global_store_dword v163, v168, s[78:79]
	v_add_u32_e32 v163, 64, v163
	global_store_dword v163, v169, s[78:79]
	v_add_u32_e32 v163, 64, v163
	global_store_dword v163, v170, s[78:79]
	v_add_u32_e32 v163, 64, v163
	global_store_dword v163, v171, s[78:79]
	v_add_u32_e32 v163, 0x140, v163
	s_waitcnt lgkmcnt(7)
	v_mul_f32_e32 v172, v36, v214
	v_mul_f32_e32 v173, v37, v215
	v_mul_f32_e32 v174, v38, v216
	v_mul_f32_e32 v175, v39, v217
	ds_read_b128 v[214:217], v141 offset:416
	global_store_dword v163, v172, s[78:79]
	v_add_u32_e32 v163, 64, v163
	global_store_dword v163, v173, s[78:79]
	v_add_u32_e32 v163, 64, v163
	global_store_dword v163, v174, s[78:79]
	v_add_u32_e32 v163, 64, v163
	global_store_dword v163, v175, s[78:79]
	v_add_u32_e32 v163, 0x140, v163
	s_waitcnt lgkmcnt(7)
	v_mul_f32_e32 v168, v40, v218
	v_mul_f32_e32 v169, v41, v219
	v_mul_f32_e32 v170, v42, v220
	v_mul_f32_e32 v171, v43, v221
	ds_read_b128 v[218:221], v141 offset:448
	global_store_dword v163, v168, s[78:79]
	v_add_u32_e32 v163, 64, v163
	global_store_dword v163, v169, s[78:79]
	v_add_u32_e32 v163, 64, v163
	global_store_dword v163, v170, s[78:79]
	v_add_u32_e32 v163, 64, v163
	global_store_dword v163, v171, s[78:79]
	v_add_u32_e32 v163, 0x140, v163
	s_waitcnt lgkmcnt(7)
	v_mul_f32_e32 v172, v44, v222
	v_mul_f32_e32 v173, v45, v223
	v_mul_f32_e32 v174, v46, v224
	v_mul_f32_e32 v175, v47, v225
	ds_read_b128 v[222:225], v141 offset:480
	global_store_dword v163, v172, s[78:79]
	v_add_u32_e32 v163, 64, v163
	global_store_dword v163, v173, s[78:79]
	v_add_u32_e32 v163, 64, v163
	global_store_dword v163, v174, s[78:79]
	v_add_u32_e32 v163, 64, v163
	global_store_dword v163, v175, s[78:79]
	v_add_u32_e32 v163, 0x140, v163
	s_waitcnt lgkmcnt(7)
	v_mul_f32_e32 v168, v16, v176
	v_mul_f32_e32 v169, v17, v177
	v_mul_f32_e32 v170, v18, v178
	v_mul_f32_e32 v171, v19, v179
	global_store_dword v163, v168, s[78:79]
	v_add_u32_e32 v163, 64, v163
	global_store_dword v163, v169, s[78:79]
	v_add_u32_e32 v163, 64, v163
	global_store_dword v163, v170, s[78:79]
	v_add_u32_e32 v163, 64, v163
	global_store_dword v163, v171, s[78:79]
	v_add_u32_e32 v163, 0x140, v163
	s_waitcnt lgkmcnt(6)
	v_mul_f32_e32 v172, v20, v180
	v_mul_f32_e32 v173, v21, v181
	v_mul_f32_e32 v174, v22, v182
	v_mul_f32_e32 v175, v23, v183
	global_store_dword v163, v172, s[78:79]
	v_add_u32_e32 v163, 64, v163
	global_store_dword v163, v173, s[78:79]
	v_add_u32_e32 v163, 64, v163
	global_store_dword v163, v174, s[78:79]
	v_add_u32_e32 v163, 64, v163
	global_store_dword v163, v175, s[78:79]
	v_add_u32_e32 v163, 0x140, v163
	s_waitcnt lgkmcnt(5)
	v_mul_f32_e32 v168, v24, v184
	v_mul_f32_e32 v169, v25, v185
	v_mul_f32_e32 v170, v26, v186
	v_mul_f32_e32 v171, v27, v187
	global_store_dword v163, v168, s[78:79]
	v_add_u32_e32 v163, 64, v163
	global_store_dword v163, v169, s[78:79]
	v_add_u32_e32 v163, 64, v163
	global_store_dword v163, v170, s[78:79]
	v_add_u32_e32 v163, 64, v163
	global_store_dword v163, v171, s[78:79]
	v_add_u32_e32 v163, 0x140, v163
	s_waitcnt lgkmcnt(4)
	v_mul_f32_e32 v172, v28, v188
	v_mul_f32_e32 v173, v29, v189
	v_mul_f32_e32 v174, v30, v190
	v_mul_f32_e32 v175, v31, v191
	global_store_dword v163, v172, s[78:79]
	v_add_u32_e32 v163, 64, v163
	global_store_dword v163, v173, s[78:79]
	v_add_u32_e32 v163, 64, v163
	global_store_dword v163, v174, s[78:79]
	v_add_u32_e32 v163, 64, v163
	global_store_dword v163, v175, s[78:79]
	v_add_u32_e32 v163, 0x140, v163
	s_waitcnt lgkmcnt(3)
	v_mul_f32_e32 v168, v0, v210
	v_mul_f32_e32 v169, v1, v211
	v_mul_f32_e32 v170, v2, v212
	v_mul_f32_e32 v171, v3, v213
	global_store_dword v163, v168, s[78:79]
	v_add_u32_e32 v163, 64, v163
	global_store_dword v163, v169, s[78:79]
	v_add_u32_e32 v163, 64, v163
	global_store_dword v163, v170, s[78:79]
	v_add_u32_e32 v163, 64, v163
	global_store_dword v163, v171, s[78:79]
	v_add_u32_e32 v163, 0x140, v163
	s_waitcnt lgkmcnt(2)
	v_mul_f32_e32 v172, v4, v214
	v_mul_f32_e32 v173, v5, v215
	v_mul_f32_e32 v174, v6, v216
	v_mul_f32_e32 v175, v7, v217
	global_store_dword v163, v172, s[78:79]
	v_add_u32_e32 v163, 64, v163
	global_store_dword v163, v173, s[78:79]
	v_add_u32_e32 v163, 64, v163
	global_store_dword v163, v174, s[78:79]
	v_add_u32_e32 v163, 64, v163
	global_store_dword v163, v175, s[78:79]
	v_add_u32_e32 v163, 0x140, v163
	s_waitcnt lgkmcnt(1)
	v_mul_f32_e32 v168, v8, v218
	v_mul_f32_e32 v169, v9, v219
	v_mul_f32_e32 v170, v10, v220
	v_mul_f32_e32 v171, v11, v221
	global_store_dword v163, v168, s[78:79]
	v_add_u32_e32 v163, 64, v163
	global_store_dword v163, v169, s[78:79]
	v_add_u32_e32 v163, 64, v163
	global_store_dword v163, v170, s[78:79]
	v_add_u32_e32 v163, 64, v163
	global_store_dword v163, v171, s[78:79]
	v_add_u32_e32 v163, 0x140, v163
	s_waitcnt lgkmcnt(0)
	v_mul_f32_e32 v172, v12, v222
	v_mul_f32_e32 v173, v13, v223
	v_mul_f32_e32 v174, v14, v224
	v_mul_f32_e32 v175, v15, v225
	global_store_dword v163, v172, s[78:79]
	v_add_u32_e32 v163, 64, v163
	global_store_dword v163, v173, s[78:79]
	v_add_u32_e32 v163, 64, v163
	global_store_dword v163, v174, s[78:79]
	v_add_u32_e32 v163, 64, v163
	global_store_dword v163, v175, s[78:79]
.Lp3g_na1:
	s_mov_b64 exec, s[48:49]
	s_andn2_saveexec_b64 s[20:21], s[10:11]
	s_cbranch_execz .LBB0_1482
